# all four GEMM K-loops: LDS-DMA saddr+voffset addressing (no per-DMA VALU 64-bit adds)
# speedup vs baseline: 1.0058x; 1.0007x over previous
.LBB0_1031:
	ds_read_b128 v[144:147], v139
	ds_read_b128 v[148:151], v139 offset:1024
	ds_read_b128 v[152:155], v139 offset:2048
	ds_read_b128 v[156:159], v139 offset:3072
	ds_read_b128 v[164:167], v140
	ds_read_b128 v[168:171], v140 offset:1024
	ds_read_b128 v[172:175], v140 offset:2048
	ds_read_b128 v[176:179], v140 offset:3072
	s_add_u32 s12, s8, s10
	s_addc_u32 s13, s9, s11
	s_add_u32 s12, s12, 0x2000100
	s_addc_u32 s13, s13, 0
	s_add_u32 s42, s27, s10
	s_addc_u32 s43, s28, s11
	s_cmpk_eq_i32 s10, 0x3f00
	s_cselect_b32 s15, s3, s13
	s_cselect_b32 s14, s2, s12
	s_cselect_b32 s13, s1, s43
	s_cselect_b32 s12, s0, s42
	s_mov_b32 m0, s30
	v_lshl_add_u64 v[160:161], v[134:135], 0, s[10:11]
	ds_read_b128 v[180:183], v141
	ds_read_b128 v[184:187], v141 offset:1024
	ds_read_b128 v[188:191], v141 offset:2048
	ds_read_b128 v[196:199], v141 offset:3072
	ds_read_b128 v[200:203], v141 offset:4096
	ds_read_b128 v[204:207], v141 offset:5120
	ds_read_b128 v[208:211], v141 offset:6144
	ds_read_b128 v[212:215], v141 offset:7168
	global_load_lds_dwordx4 v[160:161], off
	v_lshl_add_u64 v[160:161], v[136:137], 0, s[10:11]
	s_mov_b32 m0, s31
	s_nop 0
	global_load_lds_dwordx4 v[160:161], off
	s_waitcnt vmcnt(8)
	s_waitcnt lgkmcnt(0)
	s_barrier
	v_mfma_f32_16x16x32_bf16 v[126:129], v[144:147], v[180:183], v[126:129]
	v_mfma_f32_16x16x32_bf16 v[122:125], v[152:155], v[180:183], v[122:125]
	v_mfma_f32_16x16x32_bf16 v[110:113], v[144:147], v[188:191], v[110:113]
	v_mfma_f32_16x16x32_bf16 v[106:109], v[152:155], v[188:191], v[106:109]
	v_mfma_f32_16x16x32_bf16 v[94:97], v[144:147], v[200:203], v[94:97]
	v_mfma_f32_16x16x32_bf16 v[90:93], v[152:155], v[200:203], v[90:93]
	v_mfma_f32_16x16x32_bf16 v[78:81], v[144:147], v[208:211], v[78:81]
	v_mfma_f32_16x16x32_bf16 v[74:77], v[152:155], v[208:211], v[74:77]
	v_mfma_f32_16x16x32_bf16 v[126:129], v[148:151], v[184:187], v[126:129]
	v_mfma_f32_16x16x32_bf16 v[122:125], v[156:159], v[184:187], v[122:125]
	v_mfma_f32_16x16x32_bf16 v[110:113], v[148:151], v[196:199], v[110:113]
	v_mfma_f32_16x16x32_bf16 v[106:109], v[156:159], v[196:199], v[106:109]
	v_mfma_f32_16x16x32_bf16 v[94:97], v[148:151], v[204:207], v[94:97]
	v_mfma_f32_16x16x32_bf16 v[90:93], v[156:159], v[204:207], v[90:93]
	v_mfma_f32_16x16x32_bf16 v[78:81], v[148:151], v[212:215], v[78:81]
	v_mfma_f32_16x16x32_bf16 v[74:77], v[156:159], v[212:215], v[74:77]
	v_mfma_f32_16x16x32_bf16 v[118:121], v[164:167], v[180:183], v[118:121]
	v_mfma_f32_16x16x32_bf16 v[114:117], v[172:175], v[180:183], v[114:117]
	v_mfma_f32_16x16x32_bf16 v[102:105], v[164:167], v[188:191], v[102:105]
	v_mfma_f32_16x16x32_bf16 v[98:101], v[172:175], v[188:191], v[98:101]
	v_mfma_f32_16x16x32_bf16 v[86:89], v[164:167], v[200:203], v[86:89]
	v_mfma_f32_16x16x32_bf16 v[82:85], v[172:175], v[200:203], v[82:85]
	v_mfma_f32_16x16x32_bf16 v[70:73], v[164:167], v[208:211], v[70:73]
	v_mfma_f32_16x16x32_bf16 v[66:69], v[172:175], v[208:211], v[66:69]
	v_mfma_f32_16x16x32_bf16 v[118:121], v[168:171], v[184:187], v[118:121]
	v_mfma_f32_16x16x32_bf16 v[114:117], v[176:179], v[184:187], v[114:117]
	v_mfma_f32_16x16x32_bf16 v[102:105], v[168:171], v[196:199], v[102:105]
	v_mfma_f32_16x16x32_bf16 v[98:101], v[176:179], v[196:199], v[98:101]
	v_mfma_f32_16x16x32_bf16 v[86:89], v[168:171], v[204:207], v[86:89]
	v_mfma_f32_16x16x32_bf16 v[82:85], v[176:179], v[204:207], v[82:85]
	v_mfma_f32_16x16x32_bf16 v[70:73], v[168:171], v[212:215], v[70:73]
	v_mfma_f32_16x16x32_bf16 v[66:69], v[176:179], v[212:215], v[66:69]
	s_barrier
	s_mov_b32 m0, s34
	s_add_u32 s42, s12, 0x200000
	s_addc_u32 s43, s13, 0
	ds_read_b128 v[180:183], v141 offset:16384
	ds_read_b128 v[184:187], v141 offset:17408
	ds_read_b128 v[188:191], v141 offset:18432
	ds_read_b128 v[196:199], v141 offset:19456
	ds_read_b128 v[200:203], v141 offset:20480
	ds_read_b128 v[204:207], v141 offset:21504
	ds_read_b128 v[208:211], v141 offset:22528
	ds_read_b128 v[212:215], v141 offset:23552
	global_load_lds_dwordx4 v130, s[12:13]
	s_mov_b32 m0, s35
	s_nop 0
	global_load_lds_dwordx4 v132, s[12:13]
	s_mov_b32 m0, s36
	s_nop 0
	global_load_lds_dwordx4 v130, s[42:43]
	s_mov_b32 m0, s37
	s_nop 0
	global_load_lds_dwordx4 v132, s[42:43]
	s_mov_b32 m0, s20
	s_nop 0
	global_load_lds_dwordx4 v130, s[14:15]
	s_mov_b32 m0, s21
	s_nop 0
	global_load_lds_dwordx4 v132, s[14:15]
	s_waitcnt vmcnt(8)
	s_waitcnt lgkmcnt(0)
	s_barrier
	v_mfma_f32_16x16x32_bf16 v[62:65], v[144:147], v[180:183], v[62:65]
	v_mfma_f32_16x16x32_bf16 v[58:61], v[152:155], v[180:183], v[58:61]
	v_mfma_f32_16x16x32_bf16 v[46:49], v[144:147], v[188:191], v[46:49]
	v_mfma_f32_16x16x32_bf16 v[42:45], v[152:155], v[188:191], v[42:45]
	v_mfma_f32_16x16x32_bf16 v[30:33], v[144:147], v[200:203], v[30:33]
	v_mfma_f32_16x16x32_bf16 v[26:29], v[152:155], v[200:203], v[26:29]
	v_mfma_f32_16x16x32_bf16 v[14:17], v[144:147], v[208:211], v[14:17]
	v_mfma_f32_16x16x32_bf16 v[10:13], v[152:155], v[208:211], v[10:13]
	v_mfma_f32_16x16x32_bf16 v[62:65], v[148:151], v[184:187], v[62:65]
	v_mfma_f32_16x16x32_bf16 v[58:61], v[156:159], v[184:187], v[58:61]
	v_mfma_f32_16x16x32_bf16 v[46:49], v[148:151], v[196:199], v[46:49]
	v_mfma_f32_16x16x32_bf16 v[42:45], v[156:159], v[196:199], v[42:45]
	v_mfma_f32_16x16x32_bf16 v[30:33], v[148:151], v[204:207], v[30:33]
	v_mfma_f32_16x16x32_bf16 v[26:29], v[156:159], v[204:207], v[26:29]
	v_mfma_f32_16x16x32_bf16 v[14:17], v[148:151], v[212:215], v[14:17]
	v_mfma_f32_16x16x32_bf16 v[10:13], v[156:159], v[212:215], v[10:13]
	v_mfma_f32_16x16x32_bf16 v[54:57], v[164:167], v[180:183], v[54:57]
	v_mfma_f32_16x16x32_bf16 v[50:53], v[172:175], v[180:183], v[50:53]
	v_mfma_f32_16x16x32_bf16 v[38:41], v[164:167], v[188:191], v[38:41]
	v_mfma_f32_16x16x32_bf16 v[34:37], v[172:175], v[188:191], v[34:37]
	v_mfma_f32_16x16x32_bf16 v[22:25], v[164:167], v[200:203], v[22:25]
	v_mfma_f32_16x16x32_bf16 v[18:21], v[172:175], v[200:203], v[18:21]
	v_mfma_f32_16x16x32_bf16 v[6:9], v[164:167], v[208:211], v[6:9]
	v_mfma_f32_16x16x32_bf16 v[2:5], v[172:175], v[208:211], v[2:5]
	v_mfma_f32_16x16x32_bf16 v[54:57], v[168:171], v[184:187], v[54:57]
	v_mfma_f32_16x16x32_bf16 v[50:53], v[176:179], v[184:187], v[50:53]
	v_mfma_f32_16x16x32_bf16 v[38:41], v[168:171], v[196:199], v[38:41]
	v_mfma_f32_16x16x32_bf16 v[34:37], v[176:179], v[196:199], v[34:37]
	v_mfma_f32_16x16x32_bf16 v[22:25], v[168:171], v[204:207], v[22:25]
	v_mfma_f32_16x16x32_bf16 v[18:21], v[176:179], v[204:207], v[18:21]
	v_mfma_f32_16x16x32_bf16 v[6:9], v[168:171], v[212:215], v[6:9]
	v_mfma_f32_16x16x32_bf16 v[2:5], v[176:179], v[212:215], v[2:5]
	s_barrier
	ds_read_b128 v[144:147], v142
	ds_read_b128 v[148:151], v142 offset:1024
	ds_read_b128 v[152:155], v142 offset:2048
	ds_read_b128 v[156:159], v142 offset:3072
	ds_read_b128 v[164:167], v143
	ds_read_b128 v[168:171], v143 offset:1024
	ds_read_b128 v[172:175], v143 offset:2048
	ds_read_b128 v[176:179], v143 offset:3072
	s_add_u32 s14, s14, 0x200000
	s_addc_u32 s15, s15, 0
	s_mov_b32 m0, s22
	ds_read_b128 v[180:183], v141 offset:32768
	ds_read_b128 v[184:187], v141 offset:33792
	ds_read_b128 v[188:191], v141 offset:34816
	ds_read_b128 v[196:199], v141 offset:35840
	ds_read_b128 v[200:203], v141 offset:36864
	ds_read_b128 v[204:207], v141 offset:37888
	ds_read_b128 v[208:211], v141 offset:38912
	ds_read_b128 v[212:215], v141 offset:39936
	global_load_lds_dwordx4 v130, s[14:15]
	s_mov_b32 m0, s23
	s_nop 0
	global_load_lds_dwordx4 v132, s[14:15]
	s_waitcnt vmcnt(8)
	s_waitcnt lgkmcnt(0)
	s_barrier
	v_mfma_f32_16x16x32_bf16 v[126:129], v[144:147], v[180:183], v[126:129]
	v_mfma_f32_16x16x32_bf16 v[122:125], v[152:155], v[180:183], v[122:125]
	v_mfma_f32_16x16x32_bf16 v[110:113], v[144:147], v[188:191], v[110:113]
	v_mfma_f32_16x16x32_bf16 v[106:109], v[152:155], v[188:191], v[106:109]
	v_mfma_f32_16x16x32_bf16 v[94:97], v[144:147], v[200:203], v[94:97]
	v_mfma_f32_16x16x32_bf16 v[90:93], v[152:155], v[200:203], v[90:93]
	v_mfma_f32_16x16x32_bf16 v[78:81], v[144:147], v[208:211], v[78:81]
	v_mfma_f32_16x16x32_bf16 v[74:77], v[152:155], v[208:211], v[74:77]
	v_mfma_f32_16x16x32_bf16 v[126:129], v[148:151], v[184:187], v[126:129]
	v_mfma_f32_16x16x32_bf16 v[122:125], v[156:159], v[184:187], v[122:125]
	v_mfma_f32_16x16x32_bf16 v[110:113], v[148:151], v[196:199], v[110:113]
	v_mfma_f32_16x16x32_bf16 v[106:109], v[156:159], v[196:199], v[106:109]
	v_mfma_f32_16x16x32_bf16 v[94:97], v[148:151], v[204:207], v[94:97]
	v_mfma_f32_16x16x32_bf16 v[90:93], v[156:159], v[204:207], v[90:93]
	v_mfma_f32_16x16x32_bf16 v[78:81], v[148:151], v[212:215], v[78:81]
	v_mfma_f32_16x16x32_bf16 v[74:77], v[156:159], v[212:215], v[74:77]
	v_mfma_f32_16x16x32_bf16 v[118:121], v[164:167], v[180:183], v[118:121]
	v_mfma_f32_16x16x32_bf16 v[114:117], v[172:175], v[180:183], v[114:117]
	v_mfma_f32_16x16x32_bf16 v[102:105], v[164:167], v[188:191], v[102:105]
	v_mfma_f32_16x16x32_bf16 v[98:101], v[172:175], v[188:191], v[98:101]
	v_mfma_f32_16x16x32_bf16 v[86:89], v[164:167], v[200:203], v[86:89]
	v_mfma_f32_16x16x32_bf16 v[82:85], v[172:175], v[200:203], v[82:85]
	v_mfma_f32_16x16x32_bf16 v[70:73], v[164:167], v[208:211], v[70:73]
	v_mfma_f32_16x16x32_bf16 v[66:69], v[172:175], v[208:211], v[66:69]
	v_mfma_f32_16x16x32_bf16 v[118:121], v[168:171], v[184:187], v[118:121]
	v_mfma_f32_16x16x32_bf16 v[114:117], v[176:179], v[184:187], v[114:117]
	v_mfma_f32_16x16x32_bf16 v[102:105], v[168:171], v[196:199], v[102:105]
	v_mfma_f32_16x16x32_bf16 v[98:101], v[176:179], v[196:199], v[98:101]
	v_mfma_f32_16x16x32_bf16 v[86:89], v[168:171], v[204:207], v[86:89]
	v_mfma_f32_16x16x32_bf16 v[82:85], v[176:179], v[204:207], v[82:85]
	v_mfma_f32_16x16x32_bf16 v[70:73], v[168:171], v[212:215], v[70:73]
	v_mfma_f32_16x16x32_bf16 v[66:69], v[176:179], v[212:215], v[66:69]
	s_barrier
	s_mov_b32 m0, s38
	s_add_u32 s12, s12, 0x200080
	s_addc_u32 s13, s13, 0
	ds_read_b128 v[180:183], v141 offset:49152
	ds_read_b128 v[184:187], v141 offset:50176
	ds_read_b128 v[188:191], v141 offset:51200
	ds_read_b128 v[196:199], v141 offset:52224
	ds_read_b128 v[200:203], v141 offset:53248
	ds_read_b128 v[204:207], v141 offset:54272
	ds_read_b128 v[208:211], v141 offset:55296
	ds_read_b128 v[212:215], v141 offset:56320
	s_add_u32 s98, s12, 0xffe00000
	s_addc_u32 s99, s13, -1
	global_load_lds_dwordx4 v130, s[98:99]
	s_mov_b32 m0, s39
	s_nop 0
	global_load_lds_dwordx4 v132, s[98:99]
	s_mov_b32 m0, s40
	s_nop 0
	global_load_lds_dwordx4 v130, s[12:13]
	s_mov_b32 m0, s41
	s_nop 0
	global_load_lds_dwordx4 v132, s[12:13]
	s_mov_b32 m0, s25
	s_nop 0
	s_add_u32 s100, s14, 0xffe00080
	s_addc_u32 s101, s15, -1
	global_load_lds_dwordx4 v130, s[100:101]
	s_mov_b32 m0, s26
	s_nop 0
	global_load_lds_dwordx4 v132, s[100:101]
	s_waitcnt vmcnt(8)
	s_waitcnt lgkmcnt(0)
	s_barrier
	v_mfma_f32_16x16x32_bf16 v[62:65], v[144:147], v[180:183], v[62:65]
	v_mfma_f32_16x16x32_bf16 v[58:61], v[152:155], v[180:183], v[58:61]
	v_mfma_f32_16x16x32_bf16 v[46:49], v[144:147], v[188:191], v[46:49]
	v_mfma_f32_16x16x32_bf16 v[42:45], v[152:155], v[188:191], v[42:45]
	v_mfma_f32_16x16x32_bf16 v[30:33], v[144:147], v[200:203], v[30:33]
	v_mfma_f32_16x16x32_bf16 v[26:29], v[152:155], v[200:203], v[26:29]
	v_mfma_f32_16x16x32_bf16 v[14:17], v[144:147], v[208:211], v[14:17]
	v_mfma_f32_16x16x32_bf16 v[10:13], v[152:155], v[208:211], v[10:13]
	v_mfma_f32_16x16x32_bf16 v[62:65], v[148:151], v[184:187], v[62:65]
	v_mfma_f32_16x16x32_bf16 v[58:61], v[156:159], v[184:187], v[58:61]
	v_mfma_f32_16x16x32_bf16 v[46:49], v[148:151], v[196:199], v[46:49]
	v_mfma_f32_16x16x32_bf16 v[42:45], v[156:159], v[196:199], v[42:45]
	v_mfma_f32_16x16x32_bf16 v[30:33], v[148:151], v[204:207], v[30:33]
	v_mfma_f32_16x16x32_bf16 v[26:29], v[156:159], v[204:207], v[26:29]
	v_mfma_f32_16x16x32_bf16 v[14:17], v[148:151], v[212:215], v[14:17]
	v_mfma_f32_16x16x32_bf16 v[10:13], v[156:159], v[212:215], v[10:13]
	v_mfma_f32_16x16x32_bf16 v[54:57], v[164:167], v[180:183], v[54:57]
	v_mfma_f32_16x16x32_bf16 v[50:53], v[172:175], v[180:183], v[50:53]
	v_mfma_f32_16x16x32_bf16 v[38:41], v[164:167], v[188:191], v[38:41]
	v_mfma_f32_16x16x32_bf16 v[34:37], v[172:175], v[188:191], v[34:37]
	v_mfma_f32_16x16x32_bf16 v[22:25], v[164:167], v[200:203], v[22:25]
	v_mfma_f32_16x16x32_bf16 v[18:21], v[172:175], v[200:203], v[18:21]
	v_mfma_f32_16x16x32_bf16 v[6:9], v[164:167], v[208:211], v[6:9]
	v_mfma_f32_16x16x32_bf16 v[2:5], v[172:175], v[208:211], v[2:5]
	v_mfma_f32_16x16x32_bf16 v[54:57], v[168:171], v[184:187], v[54:57]
	v_mfma_f32_16x16x32_bf16 v[50:53], v[176:179], v[184:187], v[50:53]
	v_mfma_f32_16x16x32_bf16 v[38:41], v[168:171], v[196:199], v[38:41]
	v_mfma_f32_16x16x32_bf16 v[34:37], v[176:179], v[196:199], v[34:37]
	v_mfma_f32_16x16x32_bf16 v[22:25], v[168:171], v[204:207], v[22:25]
	v_mfma_f32_16x16x32_bf16 v[18:21], v[176:179], v[204:207], v[18:21]
	v_mfma_f32_16x16x32_bf16 v[6:9], v[168:171], v[212:215], v[6:9]
	v_mfma_f32_16x16x32_bf16 v[2:5], v[176:179], v[212:215], v[2:5]
	s_barrier
	s_add_i32 s29, s29, 2
	s_add_u32 s10, s10, 0x100
	s_addc_u32 s11, s11, 0
	s_cmpk_lt_u32 s29, 0x7e
	s_cbranch_scc1 .LBB0_1031
	s_waitcnt vmcnt(0)
	s_cmpk_gt_u32 s19, 0xff
	s_cbranch_scc1 .LBB0_1034
	s_barrier
